# kfin batched + early Q waits removed in retention and SB setup
# speedup vs baseline: 1.0056x; 1.0056x over previous
.LBB0_420:
	s_or_b64 exec, exec, s[6:7]
	s_mov_b64 s[6:7], s[0:1]
	v_mov_b32_e32 v0, v232
	s_waitcnt lgkmcnt(0)
	s_barrier
	v_readlane_b32 s4, v255, 2
	v_readfirstlane_b32 s9, v0
	s_ashr_i32 s8, s9, 6
	s_ashr_i32 s51, s50, 31
	s_add_i32 s8, s8, s4
	v_mov_b32_e32 v199, 1
	s_cmpk_gt_i32 s8, 0x1fff
	s_cbranch_scc1 .LBB0_423
	s_load_dwordx4 s[12:15], s[6:7], 0x58
	s_load_dwordx2 s[10:11], s[6:7], 0x90
	s_lshl_b32 s6, s50, 8
	s_ashr_i32 s7, s6, 31
	s_lshl_b64 s[6:7], s[6:7], 2
	s_waitcnt lgkmcnt(0)
	s_add_u32 s14, s14, s6
	s_addc_u32 s15, s15, s7
	s_add_u32 s6, s12, s6
	v_and_b32_e32 v6, 63, v0
	s_addc_u32 s7, s13, s7
	v_lshlrev_b32_e32 v0, 4, v6
	s_bfe_u32 s9, s9, 0x20006
	v_lshl_add_u64 v[2:3], s[6:7], 0, v[0:1]
	s_lshl_b32 s6, s9, 4
	s_add_u32 s6, s10, s6
	s_addc_u32 s7, s11, 0
	s_add_u32 s6, s6, 0xf000000
	s_addc_u32 s7, s7, 0
	s_lshl_b32 s9, s9, 9
	s_add_u32 s10, s10, s9
	v_lshl_add_u64 v[4:5], s[14:15], 0, v[0:1]
	s_addc_u32 s11, s11, 0
	v_lshlrev_b32_e32 v0, 3, v6
	v_lshl_add_u64 v[6:7], s[10:11], 0, v[0:1]
	s_mov_b64 s[10:11], 0xe200000
	v_lshl_add_u64 v[6:7], v[6:7], 0, s[10:11]
	global_load_dwordx4 v[40:43], v[2:3], off
	global_load_dwordx4 v[44:47], v[4:5], off
.LBB0_422:
	s_ashr_i32 s10, s8, 2
	s_ashr_i32 s11, s10, 31
	s_lshl_b64 s[12:13], s[10:11], 6
	s_add_u32 s12, s6, s12
	s_addc_u32 s13, s7, s13
	global_load_dwordx4 v[8:11], v1, s[12:13]
	s_lshl_b64 s[10:11], s[10:11], 12
	v_lshl_add_u64 v[32:33], v[6:7], 0, s[10:11]
	global_load_dwordx2 v[24:25], v[32:33], off
	s_add_i32 s16, s8, s93
	s_cmpk_gt_i32 s16, 0x1fff
	s_cbranch_scc1 .Lkf_issued
	s_ashr_i32 s10, s16, 2
	s_ashr_i32 s11, s10, 31
	s_lshl_b64 s[12:13], s[10:11], 6
	s_add_u32 s12, s6, s12
	s_addc_u32 s13, s7, s13
	global_load_dwordx4 v[12:15], v1, s[12:13]
	s_lshl_b64 s[10:11], s[10:11], 12
	v_lshl_add_u64 v[34:35], v[6:7], 0, s[10:11]
	global_load_dwordx2 v[26:27], v[34:35], off
	s_add_i32 s17, s16, s93
	s_cmpk_gt_i32 s17, 0x1fff
	s_cbranch_scc1 .Lkf_issued
	s_ashr_i32 s10, s17, 2
	s_ashr_i32 s11, s10, 31
	s_lshl_b64 s[12:13], s[10:11], 6
	s_add_u32 s12, s6, s12
	s_addc_u32 s13, s7, s13
	global_load_dwordx4 v[16:19], v1, s[12:13]
	s_lshl_b64 s[10:11], s[10:11], 12
	v_lshl_add_u64 v[36:37], v[6:7], 0, s[10:11]
	global_load_dwordx2 v[28:29], v[36:37], off
	s_add_i32 s18, s17, s93
	s_cmpk_gt_i32 s18, 0x1fff
	s_cbranch_scc1 .Lkf_issued
	s_ashr_i32 s10, s18, 2
	s_ashr_i32 s11, s10, 31
	s_lshl_b64 s[12:13], s[10:11], 6
	s_add_u32 s12, s6, s12
	s_addc_u32 s13, s7, s13
	global_load_dwordx4 v[20:23], v1, s[12:13]
	s_lshl_b64 s[10:11], s[10:11], 12
	v_lshl_add_u64 v[38:39], v[6:7], 0, s[10:11]
	global_load_dwordx2 v[30:31], v[38:39], off
.Lkf_issued:
	s_waitcnt vmcnt(0)
	v_mov_b32_e32 v48, v9
	v_mov_b32_e32 v49, v10
	v_mov_b32_e32 v9, v11
	v_pk_add_f32 v[50:51], v[48:49], v[8:9]
	s_nop 0
	v_add_f32_e32 v0, v50, v51
	v_fmamk_f32 v0, v0, 0x3b800000, v233
	v_cmp_gt_f32_e32 vcc, s82, v0
	v_mul_f32_e32 v48, 0x4b800000, v0
	s_nop 0
	v_cndmask_b32_e32 v0, v0, v48, vcc
	v_rsq_f32_e32 v0, v0
	s_nop 0
	v_mul_f32_e32 v48, 0x45800000, v0
	v_cndmask_b32_e32 v0, v0, v48, vcc
	v_mul_f32_e32 v0, 0x3db8aa3b, v0
	v_lshlrev_b32_e32 v52, 16, v24
	v_and_b32_e32 v53, 0xffff0000, v24
	v_lshlrev_b32_e32 v54, 16, v25
	v_and_b32_e32 v55, 0xffff0000, v25
	v_pk_mul_f32 v[52:53], v[0:1], v[52:53] op_sel_hi:[0,1]
	v_pk_mul_f32 v[54:55], v[0:1], v[54:55] op_sel_hi:[0,1]
	v_pk_mul_f32 v[52:53], v[40:41], v[52:53]
	v_pk_mul_f32 v[54:55], v[42:43], v[54:55]
	v_pk_mul_f32 v[52:53], v[44:45], v[52:53]
	v_pk_mul_f32 v[54:55], v[46:47], v[54:55]
	v_cvt_pk_bf16_f32 v8, v52, v53
	v_cvt_pk_bf16_f32 v9, v54, v55
	global_store_dwordx2 v[32:33], v[8:9], off
	s_cmpk_gt_i32 s16, 0x1fff
	s_cbranch_scc1 .Lkf_end
	v_mov_b32_e32 v48, v13
	v_mov_b32_e32 v49, v14
	v_mov_b32_e32 v13, v15
	v_pk_add_f32 v[50:51], v[48:49], v[12:13]
	s_nop 0
	v_add_f32_e32 v0, v50, v51
	v_fmamk_f32 v0, v0, 0x3b800000, v233
	v_cmp_gt_f32_e32 vcc, s82, v0
	v_mul_f32_e32 v48, 0x4b800000, v0
	s_nop 0
	v_cndmask_b32_e32 v0, v0, v48, vcc
	v_rsq_f32_e32 v0, v0
	s_nop 0
	v_mul_f32_e32 v48, 0x45800000, v0
	v_cndmask_b32_e32 v0, v0, v48, vcc
	v_mul_f32_e32 v0, 0x3db8aa3b, v0
	v_lshlrev_b32_e32 v52, 16, v26
	v_and_b32_e32 v53, 0xffff0000, v26
	v_lshlrev_b32_e32 v54, 16, v27
	v_and_b32_e32 v55, 0xffff0000, v27
	v_pk_mul_f32 v[52:53], v[0:1], v[52:53] op_sel_hi:[0,1]
	v_pk_mul_f32 v[54:55], v[0:1], v[54:55] op_sel_hi:[0,1]
	v_pk_mul_f32 v[52:53], v[40:41], v[52:53]
	v_pk_mul_f32 v[54:55], v[42:43], v[54:55]
	v_pk_mul_f32 v[52:53], v[44:45], v[52:53]
	v_pk_mul_f32 v[54:55], v[46:47], v[54:55]
	v_cvt_pk_bf16_f32 v12, v52, v53
	v_cvt_pk_bf16_f32 v13, v54, v55
	global_store_dwordx2 v[34:35], v[12:13], off
	s_cmpk_gt_i32 s17, 0x1fff
	s_cbranch_scc1 .Lkf_end
	v_mov_b32_e32 v48, v17
	v_mov_b32_e32 v49, v18
	v_mov_b32_e32 v17, v19
	v_pk_add_f32 v[50:51], v[48:49], v[16:17]
	s_nop 0
	v_add_f32_e32 v0, v50, v51
	v_fmamk_f32 v0, v0, 0x3b800000, v233
	v_cmp_gt_f32_e32 vcc, s82, v0
	v_mul_f32_e32 v48, 0x4b800000, v0
	s_nop 0
	v_cndmask_b32_e32 v0, v0, v48, vcc
	v_rsq_f32_e32 v0, v0
	s_nop 0
	v_mul_f32_e32 v48, 0x45800000, v0
	v_cndmask_b32_e32 v0, v0, v48, vcc
	v_mul_f32_e32 v0, 0x3db8aa3b, v0
	v_lshlrev_b32_e32 v52, 16, v28
	v_and_b32_e32 v53, 0xffff0000, v28
	v_lshlrev_b32_e32 v54, 16, v29
	v_and_b32_e32 v55, 0xffff0000, v29
	v_pk_mul_f32 v[52:53], v[0:1], v[52:53] op_sel_hi:[0,1]
	v_pk_mul_f32 v[54:55], v[0:1], v[54:55] op_sel_hi:[0,1]
	v_pk_mul_f32 v[52:53], v[40:41], v[52:53]
	v_pk_mul_f32 v[54:55], v[42:43], v[54:55]
	v_pk_mul_f32 v[52:53], v[44:45], v[52:53]
	v_pk_mul_f32 v[54:55], v[46:47], v[54:55]
	v_cvt_pk_bf16_f32 v16, v52, v53
	v_cvt_pk_bf16_f32 v17, v54, v55
	global_store_dwordx2 v[36:37], v[16:17], off
	s_cmpk_gt_i32 s18, 0x1fff
	s_cbranch_scc1 .Lkf_end
	v_mov_b32_e32 v48, v21
	v_mov_b32_e32 v49, v22
	v_mov_b32_e32 v21, v23
	v_pk_add_f32 v[50:51], v[48:49], v[20:21]
	s_nop 0
	v_add_f32_e32 v0, v50, v51
	v_fmamk_f32 v0, v0, 0x3b800000, v233
	v_cmp_gt_f32_e32 vcc, s82, v0
	v_mul_f32_e32 v48, 0x4b800000, v0
	s_nop 0
	v_cndmask_b32_e32 v0, v0, v48, vcc
	v_rsq_f32_e32 v0, v0
	s_nop 0
	v_mul_f32_e32 v48, 0x45800000, v0
	v_cndmask_b32_e32 v0, v0, v48, vcc
	v_mul_f32_e32 v0, 0x3db8aa3b, v0
	v_lshlrev_b32_e32 v52, 16, v30
	v_and_b32_e32 v53, 0xffff0000, v30
	v_lshlrev_b32_e32 v54, 16, v31
	v_and_b32_e32 v55, 0xffff0000, v31
	v_pk_mul_f32 v[52:53], v[0:1], v[52:53] op_sel_hi:[0,1]
	v_pk_mul_f32 v[54:55], v[0:1], v[54:55] op_sel_hi:[0,1]
	v_pk_mul_f32 v[52:53], v[40:41], v[52:53]
	v_pk_mul_f32 v[54:55], v[42:43], v[54:55]
	v_pk_mul_f32 v[52:53], v[44:45], v[52:53]
	v_pk_mul_f32 v[54:55], v[46:47], v[54:55]
	v_cvt_pk_bf16_f32 v20, v52, v53
	v_cvt_pk_bf16_f32 v21, v54, v55
	global_store_dwordx2 v[38:39], v[20:21], off
	s_add_i32 s8, s18, s93
	s_cmpk_gt_i32 s8, 0x1fff
	s_cbranch_scc0 .LBB0_422
.Lkf_end:
.LBB0_423:
	s_mov_b64 s[8:9], s[0:1]
	s_load_dwordx2 s[10:11], s[8:9], 0x90
	v_readlane_b32 s4, v255, 7
	v_readlane_b32 s5, v255, 8
	v_mov_b32_e32 v228, v232
	s_andn2_b64 vcc, exec, s[4:5]
	v_cndmask_b32_e64 v0, 0, 1, s[4:5]
	v_cmp_ne_u32_e64 s[6:7], 1, v0
	s_cbranch_vccnz .LBB0_447
	s_load_dwordx2 s[8:9], s[8:9], 0x20
	s_lshl_b32 s12, s50, 9
	s_ashr_i32 s13, s12, 31
	s_lshl_b64 s[12:13], s[12:13], 2
	v_readlane_b32 s26, v255, 48
	s_waitcnt lgkmcnt(0)
	s_add_u32 s24, s8, s12
	s_addc_u32 s25, s9, s13
	s_add_u32 s8, s10, 0x6200000
	s_addc_u32 s9, s11, 0
	s_mov_b32 s27, s2
	s_branch .LBB0_427

.LBB0_427:
	s_ashr_i32 s14, s27, 6
	v_cvt_f32_i32_e32 v0, s14
	s_mov_b32 s13, 0xc2fc0000
	v_mov_b32_e32 v2, 0x42800000
	s_bfe_u32 s35, s27, 0x30003
	v_sub_f32_e32 v0, 0xc0a00000, v0
	v_cmp_gt_f32_e32 vcc, s13, v0
	s_mul_i32 s12, s35, 0x1c0000
	s_add_u32 s36, s12, 0x70000
	v_cndmask_b32_e32 v2, 0, v2, vcc
	v_add_f32_e32 v0, v0, v2
	v_exp_f32_e32 v0, v0
	s_and_b64 s[12:13], vcc, exec
	s_cselect_b32 s12, 0xffffffc0, 0
	v_mov_b32_e32 v16, v232
	v_ldexp_f32 v0, v0, s12
	v_sub_f32_e32 v8, 1.0, v0
	v_cmp_gt_f32_e32 vcc, s82, v8
	s_and_b64 s[12:13], vcc, exec
	s_cselect_b32 s16, 32, 0
	v_readfirstlane_b32 s12, v16
	s_ashr_i32 s17, s12, 6
	s_lshl_b32 s13, s27, 11
	s_and_b32 s76, s13, 0x3800
	s_lshl_b32 s28, s35, 8
	s_lshl_b32 s13, s17, 5
	v_and_b32_e32 v229, 31, v16
	s_add_i32 s28, s28, s13
	v_or_b32_e32 v130, s28, v229
	v_ashrrev_i32_e32 v131, 31, v130
	v_lshl_add_u64 v[4:5], v[130:131], 0, s[76:77]
	v_mov_b64_e32 v[2:3], s[8:9]
	s_lshl_b32 s12, s14, 7
	v_mad_u64_u32 v[6:7], s[14:15], v4, s83, v[2:3]
	v_mov_b32_e32 v0, 0x42000000
	v_bfe_u32 v17, v16, 5, 1
	v_mad_i32_i24 v7, v5, s83, v7
	s_ashr_i32 s13, s12, 31
	v_cndmask_b32_e32 v9, 0, v0, vcc
	v_lshl_add_u64 v[4:5], s[12:13], 1, v[6:7]
	v_lshlrev_b32_e32 v0, 4, v17
	v_lshl_add_u64 v[4:5], v[4:5], 0, v[0:1]
	global_load_dwordx4 v[126:129], v[4:5], off
	global_load_dwordx4 v[122:125], v[4:5], off offset:32
	global_load_dwordx4 v[118:121], v[4:5], off offset:64
	global_load_dwordx4 v[114:117], v[4:5], off offset:96
	global_load_dwordx4 v[110:113], v[4:5], off offset:128
	global_load_dwordx4 v[106:109], v[4:5], off offset:160
	global_load_dwordx4 v[102:105], v[4:5], off offset:192
	global_load_dwordx4 v[98:101], v[4:5], off offset:224
	v_bfe_u32 v4, v16, 4, 2
	v_lshlrev_b32_e32 v0, 2, v4
	v_bitop3_b32 v0, v0, v16, 12 bitop3:0x78
	v_and_or_b32 v12, v16, 3, v0
	v_ldexp_f32 v0, v8, s16
	s_ashr_i32 s16, s17, 31
	s_bfe_i32 s18, s17, 0x1001d
	s_lshl_b32 s43, s17, 2
	s_lshr_b32 s16, s16, 30
	s_lshr_b32 s42, s18, 28
	s_add_i32 s19, s17, s16
	s_add_i32 s16, s43, s42
	s_and_b32 s16, s16, -16
	s_add_i32 s14, s12, 0x200
	s_add_i32 s34, s12, 0x400
	v_log_f32_e32 v0, v0
	s_add_i32 s18, s43, 15
	s_sub_i32 s20, s43, s16
	s_cmp_lt_u32 s18, 31
	s_cselect_b64 vcc, -1, 0
	v_bitop3_b32 v6, v4, v16, 15 bitop3:0x78
	v_lshl_or_b32 v164, s20, 2, v4
	s_and_b64 s[16:17], vcc, exec
	v_sub_f32_e32 v230, v0, v9
	v_cndmask_b32_e32 v0, v12, v6, vcc
	v_add_u32_e32 v6, s76, v164
	s_cselect_b32 s16, s14, s34
	s_lshl_b32 s18, s19, 12
	v_mul_hi_i32_i24_e32 v7, 0x1c00, v6
	v_mul_i32_i24_e32 v6, 0x1c00, v6
	s_lshl_b32 s29, s20, 10
	s_ashr_i32 s17, s16, 31
	s_and_b32 s18, s18, 0xffffc000
	v_lshl_add_u64 v[6:7], s[8:9], 0, v[6:7]
	s_lshl_b64 s[16:17], s[16:17], 1
	s_add_i32 s29, s29, s18
	v_lshlrev_b32_e32 v0, 4, v0
	s_or_b32 s37, s43, 1
	v_lshl_add_u64 v[6:7], v[6:7], 0, s[16:17]
	s_add_i32 s18, s29, 0
	v_lshl_add_u64 v[6:7], v[6:7], 0, v[0:1]
	s_mov_b32 s15, 0
	v_mul_f32_e32 v14, 0xc2000000, v230
	v_exp_f32_e32 v243, v14
	v_and_b32_e32 v5, 15, v16
	v_lshlrev_b32_e32 v131, 2, v17
	v_mul_f32_e32 v18, 0xc1000000, v230
	v_exp_f32_e64 v242, -v230
	v_exp_f32_e32 v244, v18
	v_mov_b64_e32 v[196:197], 0x3ff
	v_mov_b64_e32 v[200:201], 0x400
	v_ashrrev_i32_e32 v165, 31, v164
	v_lshlrev_b32_e32 v250, 8, v229
	v_sub_u32_e32 v198, v130, v131
	s_barrier
	s_mov_b32 s19, m0
	s_mov_b32 m0, s18
	s_nop 0
	global_load_lds_dwordx4 v[6:7], off
	s_mov_b32 m0, s19
	s_add_i32 s18, s37, s42
	s_ashr_i32 s38, s18, 4
	s_and_b32 s18, s18, -16
	s_sub_i32 s22, s37, s18
	s_add_i32 s18, s43, 16
	v_lshl_or_b32 v166, s22, 2, v4
	s_cmp_lt_u32 s18, 31
	v_bitop3_b32 v6, v166, 15, v16 bitop3:0x48
	s_cselect_b64 vcc, -1, 0
	v_ashrrev_i32_e32 v167, 31, v166
	v_cndmask_b32_e32 v10, v12, v6, vcc
	s_and_b64 s[18:19], vcc, exec
	v_lshl_add_u64 v[6:7], v[166:167], 0, s[76:77]
	s_cselect_b32 s18, s14, s34
	v_mad_u64_u32 v[8:9], s[20:21], v6, s83, v[2:3]
	s_ashr_i32 s19, s18, 31
	s_lshl_b32 s20, s38, 14
	s_lshl_b32 s30, s22, 10
	v_mad_i32_i24 v9, v7, s83, v9
	s_lshl_b64 s[18:19], s[18:19], 1
	s_add_i32 s30, s30, s20
	v_lshl_add_u64 v[6:7], v[8:9], 0, s[18:19]
	v_lshlrev_b32_e32 v8, 4, v10
	v_mov_b32_e32 v9, v1
	s_add_i32 s20, s30, 0
	s_or_b32 s39, s43, 2
	v_lshl_add_u64 v[6:7], v[6:7], 0, v[8:9]
	s_mov_b32 s21, m0
	s_mov_b32 m0, s20
	s_nop 0
	global_load_lds_dwordx4 v[6:7], off
	s_mov_b32 m0, s21
	s_add_i32 s20, s39, s42
	s_ashr_i32 s40, s20, 4
	s_and_b32 s20, s20, -16
	s_sub_i32 s31, s39, s20
	s_add_i32 s20, s43, 17
	v_lshl_or_b32 v168, s31, 2, v4
	s_cmp_lt_u32 s20, 31
	v_bitop3_b32 v6, v168, 15, v16 bitop3:0x48
	s_cselect_b64 vcc, -1, 0
	v_ashrrev_i32_e32 v169, 31, v168
	v_cndmask_b32_e32 v13, v12, v6, vcc
	s_and_b64 s[20:21], vcc, exec
	v_lshl_add_u64 v[6:7], v[168:169], 0, s[76:77]
	s_cselect_b32 s20, s14, s34
	v_mad_u64_u32 v[10:11], s[22:23], v6, s83, v[2:3]
	s_ashr_i32 s21, s20, 31
	s_lshl_b32 s22, s40, 14
	s_lshl_b32 s31, s31, 10
	v_mad_i32_i24 v11, v7, s83, v11
	s_lshl_b64 s[20:21], s[20:21], 1
	s_add_i32 s31, s31, s22
	v_lshl_add_u64 v[6:7], v[10:11], 0, s[20:21]
	v_lshlrev_b32_e32 v10, 4, v13
	v_mov_b32_e32 v11, v1
	s_add_i32 s22, s31, 0
	s_or_b32 s41, s43, 3
	v_lshl_add_u64 v[6:7], v[6:7], 0, v[10:11]
	s_mov_b32 s23, m0
	s_mov_b32 m0, s22
	s_nop 0
	global_load_lds_dwordx4 v[6:7], off
	s_mov_b32 m0, s23
	s_add_i32 s22, s41, s42
	s_ashr_i32 s42, s22, 4
	s_and_b32 s22, s22, -16
	s_sub_i32 s55, s41, s22
	s_add_i32 s43, s43, 18
	s_cmp_lt_u32 s43, 31
	v_lshl_or_b32 v170, s55, 2, v4
	s_cselect_b64 vcc, -1, 0
	v_bitop3_b32 v6, v170, 15, v16 bitop3:0x48
	s_and_b64 s[22:23], vcc, exec
	v_ashrrev_i32_e32 v171, 31, v170
	v_cndmask_b32_e32 v15, v12, v6, vcc
	s_cselect_b32 s22, s14, s34
	v_lshl_add_u64 v[6:7], v[170:171], 0, s[76:77]
	v_mad_u64_u32 v[12:13], s[44:45], v6, s83, v[2:3]
	s_ashr_i32 s23, s22, 31
	s_lshl_b32 s14, s42, 14
	s_lshl_b32 s34, s55, 10
	v_mad_i32_i24 v13, v7, s83, v13
	s_lshl_b64 s[22:23], s[22:23], 1
	s_add_i32 s34, s34, s14
	v_lshl_add_u64 v[6:7], v[12:13], 0, s[22:23]
	v_lshlrev_b32_e32 v12, 4, v15
	v_mov_b32_e32 v13, v1
	s_add_i32 s14, s34, 0
	v_lshl_add_u64 v[6:7], v[6:7], 0, v[12:13]
	s_mov_b32 s43, m0
	s_mov_b32 m0, s14
	s_nop 0
	global_load_lds_dwordx4 v[6:7], off
	s_mov_b32 m0, s43
	s_or_b32 s14, s76, 64
	v_add_u32_e32 v6, s14, v164
	v_mul_hi_i32_i24_e32 v7, 0x1c00, v6
	v_mul_i32_i24_e32 v6, 0x1c00, v6
	v_lshl_add_u64 v[6:7], s[8:9], 0, v[6:7]
	v_lshl_add_u64 v[6:7], v[6:7], 0, s[16:17]
	v_lshl_add_u64 v[6:7], v[6:7], 0, v[0:1]
	s_add_i32 s43, 0, 0x8000
	s_add_i32 s44, s29, s43
	s_mov_b32 s45, m0
	s_mov_b32 m0, s44
	s_nop 0
	global_load_lds_dwordx4 v[6:7], off
	s_mov_b32 m0, s45
	v_lshl_add_u64 v[6:7], s[14:15], 0, v[166:167]
	v_mad_u64_u32 v[14:15], s[44:45], v6, s83, v[2:3]
	v_mad_i32_i24 v15, v7, s83, v15
	v_lshl_add_u64 v[6:7], v[14:15], 0, s[18:19]
	v_lshl_add_u64 v[6:7], v[6:7], 0, v[8:9]
	s_add_i32 s44, s30, s43
	s_mov_b32 s45, m0
	s_mov_b32 m0, s44
	s_nop 0
	global_load_lds_dwordx4 v[6:7], off
	s_mov_b32 m0, s45
	v_lshl_add_u64 v[6:7], s[14:15], 0, v[168:169]
	v_mad_u64_u32 v[14:15], s[44:45], v6, s83, v[2:3]
	v_mad_i32_i24 v15, v7, s83, v15
	v_lshl_add_u64 v[6:7], v[14:15], 0, s[20:21]
	v_lshl_add_u64 v[6:7], v[6:7], 0, v[10:11]
	s_add_i32 s44, s31, s43
	s_mov_b32 s45, m0
	s_mov_b32 m0, s44
	s_nop 0
	global_load_lds_dwordx4 v[6:7], off
	s_mov_b32 m0, s45
	v_lshl_add_u64 v[6:7], s[14:15], 0, v[170:171]
	v_mad_u64_u32 v[14:15], s[44:45], v6, s83, v[2:3]
	v_mad_i32_i24 v15, v7, s83, v15
	v_lshl_add_u64 v[6:7], v[14:15], 0, s[22:23]
	s_add_i32 s14, s34, s43
	v_lshl_add_u64 v[6:7], v[6:7], 0, v[12:13]
	s_mov_b32 s43, m0
	s_mov_b32 m0, s14
	s_nop 0
	global_load_lds_dwordx4 v[6:7], off
	s_mov_b32 m0, s43
	s_or_b32 s14, s76, 0x80
	v_add_u32_e32 v6, s14, v164
	v_mul_hi_i32_i24_e32 v7, 0x1c00, v6
	v_mul_i32_i24_e32 v6, 0x1c00, v6
	v_lshl_add_u64 v[6:7], s[8:9], 0, v[6:7]
	v_lshl_add_u64 v[6:7], v[6:7], 0, s[16:17]
	v_lshl_add_u64 v[6:7], v[6:7], 0, v[0:1]
	s_add_i32 s43, 0, 0x10000
	s_add_i32 s44, s29, s43
	s_mov_b32 s45, m0
	s_mov_b32 m0, s44
	s_nop 0
	global_load_lds_dwordx4 v[6:7], off
	s_mov_b32 m0, s45
	v_lshl_add_u64 v[6:7], s[14:15], 0, v[166:167]
	v_mad_u64_u32 v[14:15], s[44:45], v6, s83, v[2:3]
	v_mad_i32_i24 v15, v7, s83, v15
	v_lshl_add_u64 v[6:7], v[14:15], 0, s[18:19]
	v_lshl_add_u64 v[6:7], v[6:7], 0, v[8:9]
	s_add_i32 s44, s30, s43
	s_mov_b32 s45, m0
	s_mov_b32 m0, s44
	s_nop 0
	global_load_lds_dwordx4 v[6:7], off
	s_mov_b32 m0, s45
	v_lshl_add_u64 v[6:7], s[14:15], 0, v[168:169]
	v_mad_u64_u32 v[14:15], s[44:45], v6, s83, v[2:3]
	v_mad_i32_i24 v15, v7, s83, v15
	v_lshl_add_u64 v[6:7], v[14:15], 0, s[20:21]
	v_lshl_add_u64 v[6:7], v[6:7], 0, v[10:11]
	s_add_i32 s44, s31, s43
	s_mov_b32 s45, m0
	s_mov_b32 m0, s44
	s_nop 0
	global_load_lds_dwordx4 v[6:7], off
	s_mov_b32 m0, s45
	v_lshl_add_u64 v[6:7], s[14:15], 0, v[170:171]
	v_mad_u64_u32 v[2:3], s[44:45], v6, s83, v[2:3]
	v_mad_i32_i24 v3, v7, s83, v3
	v_lshl_add_u64 v[2:3], v[2:3], 0, s[22:23]
	s_add_i32 s14, s34, s43
	v_lshl_add_u64 v[2:3], v[2:3], 0, v[12:13]
	s_mov_b32 s43, m0
	s_mov_b32 m0, s14
	s_nop 0
	global_load_lds_dwordx4 v[2:3], off
	s_mov_b32 m0, s43
	s_ashr_i32 s14, s28, 6
	s_add_u32 s16, s8, s16
	s_addc_u32 s17, s9, s17
	v_lshl_add_u64 v[178:179], s[16:17], 0, v[0:1]
	s_add_u32 s16, s8, s18
	s_addc_u32 s17, s9, s19
	v_bitop3_b32 v0, v17, v16, 15 bitop3:0x78
	v_lshl_add_u64 v[176:177], s[16:17], 0, v[8:9]
	s_add_u32 s16, s8, s20
	v_lshlrev_b32_e32 v237, 4, v0
	v_bitop3_b32 v0, v17, v5, 2 bitop3:0x36
	s_addc_u32 s17, s9, s21
	v_lshlrev_b32_e32 v235, 4, v0
	v_bitop3_b32 v0, v17, v5, 4 bitop3:0x36
	v_lshl_add_u64 v[174:175], s[16:17], 0, v[10:11]
	s_add_u32 s16, s8, s22
	v_lshlrev_b32_e32 v234, 4, v0
	v_bitop3_b32 v0, v17, v5, 6 bitop3:0x36
	v_lshlrev_b32_e32 v3, 1, v16
	s_addc_u32 s17, s9, s23
	v_lshlrev_b32_e32 v236, 4, v0
	v_bitop3_b32 v0, v17, v5, 8 bitop3:0x36
	v_and_b32_e32 v231, 32, v3
	v_lshlrev_b32_e32 v3, 3, v16
	v_lshl_add_u64 v[172:173], s[16:17], 0, v[12:13]
	v_lshlrev_b32_e32 v253, 4, v0
	v_bitop3_b32 v0, v17, v5, 10 bitop3:0x36
	s_and_b32 s16, s28, 0xffffffc0
	v_and_b32_e32 v241, 24, v3
	v_lshlrev_b32_e32 v252, 4, v0
	v_bitop3_b32 v0, v17, v5, 12 bitop3:0x36
	v_or_b32_e32 v3, s16, v131
	v_lshlrev_b32_e32 v251, 4, v0
	v_bitop3_b32 v0, v17, v5, 14 bitop3:0x36
	v_sub_u32_e32 v5, v130, v3
	v_subrev_u32_e32 v6, 32, v5
	v_cvt_f32_i32_e32 v6, v6
	s_movk_i32 s16, 0xffdf
	v_xad_u32 v7, v3, s16, v130
	v_cvt_f32_i32_e32 v7, v7
	v_lshlrev_b32_e32 v254, 4, v0
	v_mul_f32_e64 v0, v230, |v6|
	v_subrev_u32_e32 v6, 34, v5
	v_cvt_f32_i32_e32 v6, v6
	v_exp_f32_e32 v132, v0
	v_mul_f32_e64 v0, v230, |v7|
	v_subrev_u32_e32 v7, 35, v5
	v_cvt_f32_i32_e32 v7, v7
	v_exp_f32_e32 v133, v0
	v_mul_f32_e64 v0, v230, |v6|
	v_subrev_u32_e32 v6, 40, v5
	v_cvt_f32_i32_e32 v6, v6
	v_exp_f32_e32 v134, v0
	v_mul_f32_e64 v0, v230, |v7|
	v_subrev_u32_e32 v7, 41, v5
	v_cvt_f32_i32_e32 v7, v7
	v_exp_f32_e32 v135, v0
	v_mul_f32_e64 v0, v230, |v6|
	v_subrev_u32_e32 v6, 42, v5
	v_cvt_f32_i32_e32 v6, v6
	v_exp_f32_e32 v136, v0
	v_mul_f32_e64 v0, v230, |v7|
	v_subrev_u32_e32 v7, 43, v5
	v_cvt_f32_i32_e32 v7, v7
	v_exp_f32_e32 v137, v0
	v_mul_f32_e64 v0, v230, |v6|
	v_subrev_u32_e32 v6, 48, v5
	v_cvt_f32_i32_e32 v6, v6
	v_exp_f32_e32 v138, v0
	v_mul_f32_e64 v0, v230, |v7|
	v_subrev_u32_e32 v7, 49, v5
	v_cvt_f32_i32_e32 v7, v7
	v_exp_f32_e32 v139, v0
	v_mul_f32_e64 v0, v230, |v6|
	v_subrev_u32_e32 v6, 50, v5
	v_cvt_f32_i32_e32 v6, v6
	v_exp_f32_e32 v140, v0
	v_mul_f32_e64 v0, v230, |v7|
	v_subrev_u32_e32 v7, 51, v5
	v_cvt_f32_i32_e32 v7, v7
	v_exp_f32_e32 v141, v0
	v_mul_f32_e64 v0, v230, |v6|
	v_subrev_u32_e32 v6, 56, v5
	v_cvt_f32_i32_e32 v6, v6
	v_exp_f32_e32 v142, v0
	v_mul_f32_e64 v0, v230, |v7|
	v_subrev_u32_e32 v7, 57, v5
	v_cvt_f32_i32_e32 v7, v7
	v_exp_f32_e32 v143, v0
	v_mul_f32_e64 v0, v230, |v6|
	v_subrev_u32_e32 v6, 58, v5
	v_cvt_f32_i32_e32 v6, v6
	v_exp_f32_e32 v146, v0
	v_mul_f32_e64 v0, v230, |v7|
	v_subrev_u32_e32 v7, 59, v5
	v_cvt_f32_i32_e32 v7, v7
	v_exp_f32_e32 v147, v0
	v_mul_f32_e64 v0, v230, |v6|
	v_cvt_f32_i32_e32 v6, v5
	v_xad_u32 v3, v3, -1, v130
	v_cvt_f32_i32_e32 v3, v3
	v_exp_f32_e32 v148, v0
	v_mul_f32_e64 v0, v230, |v7|
	v_exp_f32_e32 v149, v0
	v_mul_f32_e64 v0, v230, |v6|
	v_exp_f32_e32 v144, v0
	v_mul_f32_e64 v0, v230, |v3|
	v_add_u32_e32 v3, -2, v5
	v_cvt_f32_i32_e32 v3, v3
	v_add_u32_e32 v6, -3, v5
	v_cvt_f32_i32_e32 v6, v6
	v_exp_f32_e32 v145, v0
	v_mul_f32_e64 v0, v230, |v3|
	v_add_u32_e32 v3, -8, v5
	v_cvt_f32_i32_e32 v3, v3
	v_exp_f32_e32 v150, v0
	v_mul_f32_e64 v0, v230, |v6|
	v_add_u32_e32 v6, -9, v5
	v_cvt_f32_i32_e32 v6, v6
	v_exp_f32_e32 v151, v0
	v_mul_f32_e64 v0, v230, |v3|
	v_add_u32_e32 v3, -10, v5
	v_cvt_f32_i32_e32 v3, v3
	v_exp_f32_e32 v152, v0
	v_mul_f32_e64 v0, v230, |v6|
	v_add_u32_e32 v6, -11, v5
	v_cvt_f32_i32_e32 v6, v6
	v_exp_f32_e32 v153, v0
	v_mul_f32_e64 v0, v230, |v3|
	v_add_u32_e32 v3, -16, v5
	v_cvt_f32_i32_e32 v3, v3
	v_exp_f32_e32 v154, v0
	v_mul_f32_e64 v0, v230, |v6|
	v_subrev_u32_e32 v6, 17, v5
	v_cvt_f32_i32_e32 v6, v6
	v_exp_f32_e32 v155, v0
	v_mul_f32_e64 v0, v230, |v3|
	v_subrev_u32_e32 v3, 18, v5
	v_cvt_f32_i32_e32 v3, v3
	v_exp_f32_e32 v156, v0
	v_mul_f32_e64 v0, v230, |v6|
	v_subrev_u32_e32 v6, 19, v5
	v_cvt_f32_i32_e32 v6, v6
	v_exp_f32_e32 v157, v0
	v_mul_f32_e64 v0, v230, |v3|
	v_subrev_u32_e32 v3, 24, v5
	v_cvt_f32_i32_e32 v3, v3
	v_exp_f32_e32 v158, v0
	v_mul_f32_e64 v0, v230, |v6|
	v_subrev_u32_e32 v6, 25, v5
	v_cvt_f32_i32_e32 v6, v6
	v_exp_f32_e32 v159, v0
	v_mul_f32_e64 v0, v230, |v3|
	v_subrev_u32_e32 v3, 26, v5
	v_cvt_f32_i32_e32 v3, v3
	v_subrev_u32_e32 v5, 27, v5
	v_cvt_f32_i32_e32 v5, v5
	v_exp_f32_e32 v160, v0
	v_mul_f32_e64 v0, v230, |v6|
	v_exp_f32_e32 v161, v0
	v_mul_f32_e64 v0, v230, |v3|
	v_bfe_u32 v2, v16, 2, 2
	v_exp_f32_e32 v162, v0
	v_mul_f32_e64 v0, v230, |v5|
	v_exp_f32_e32 v163, v0
	v_or_b32_e32 v0, v131, v2
	v_lshlrev_b32_e32 v248, 8, v0
	v_lshl_or_b32 v0, s41, 2, v4
	s_lshl_b32 s16, s42, 6
	v_subrev_u32_e32 v0, s16, v0
	v_lshlrev_b32_e32 v249, 6, v2
	v_mad_i64_i32 v[2:3], s[16:17], v0, s83, 0
	s_bfe_u32 s18, s26, 0x3000b
	v_mad_u64_u32 v[2:3], s[16:17], s18, v239, v[2:3]
	v_lshl_or_b32 v0, s39, 2, v4
	s_lshl_b32 s16, s40, 6
	v_lshl_add_u64 v[2:3], v[172:173], 0, v[2:3]
	v_subrev_u32_e32 v0, s16, v0
	v_lshl_add_u64 v[180:181], v[2:3], 0, s[94:95]
	v_mad_i64_i32 v[2:3], s[16:17], v0, s83, 0
	v_mad_u64_u32 v[2:3], s[16:17], s18, v239, v[2:3]
	v_lshl_or_b32 v0, s37, 2, v4
	s_lshl_b32 s16, s38, 6
	v_lshl_add_u64 v[2:3], v[174:175], 0, v[2:3]
	v_subrev_u32_e32 v0, s16, v0
	v_lshl_add_u64 v[182:183], v[2:3], 0, s[94:95]
	v_mad_i64_i32 v[2:3], s[16:17], v0, s83, 0
	v_mad_u64_u32 v[2:3], s[16:17], s18, v239, v[2:3]
	v_lshl_add_u64 v[2:3], v[176:177], 0, v[2:3]
	v_lshl_add_u64 v[184:185], v[2:3], 0, s[94:95]
	v_mad_i64_i32 v[2:3], s[16:17], v164, s83, 0
	v_mad_u64_u32 v[2:3], s[16:17], s18, v239, v[2:3]
	v_lshl_add_u64 v[2:3], v[178:179], 0, v[2:3]
	v_mov_b32_e32 v14, v1
	v_mov_b32_e32 v15, v1
	v_lshl_add_u64 v[186:187], v[2:3], 0, s[94:95]
	v_mov_b32_e32 v0, v1
	v_mov_b32_e32 v2, v1
	v_mov_b32_e32 v3, v1
	v_mov_b32_e32 v4, v1
	v_mov_b32_e32 v5, v1
	v_mov_b32_e32 v6, v1
	v_mov_b32_e32 v7, v1
	v_mov_b32_e32 v8, v1
	v_mov_b32_e32 v10, v1
	v_mov_b32_e32 v12, v1
	v_mov_b64_e32 v[64:65], v[14:15]
	v_mov_b64_e32 v[48:49], v[14:15]
	v_mov_b64_e32 v[32:33], v[14:15]
	v_mov_b64_e32 v[62:63], v[12:13]
	v_mov_b64_e32 v[60:61], v[10:11]
	v_mov_b64_e32 v[58:59], v[8:9]
	v_mov_b64_e32 v[56:57], v[6:7]
	v_mov_b64_e32 v[54:55], v[4:5]
	v_mov_b64_e32 v[52:53], v[2:3]
	v_mov_b64_e32 v[50:51], v[0:1]
	v_mov_b64_e32 v[46:47], v[12:13]
	v_mov_b64_e32 v[44:45], v[10:11]
	v_mov_b64_e32 v[42:43], v[8:9]
	v_mov_b64_e32 v[40:41], v[6:7]
	v_mov_b64_e32 v[38:39], v[4:5]
	v_mov_b64_e32 v[36:37], v[2:3]
	v_mov_b64_e32 v[34:35], v[0:1]
	v_mov_b64_e32 v[30:31], v[12:13]
	v_mov_b64_e32 v[28:29], v[10:11]
	v_mov_b64_e32 v[26:27], v[8:9]
	v_mov_b64_e32 v[24:25], v[6:7]
	v_mov_b64_e32 v[22:23], v[4:5]
	v_mov_b64_e32 v[20:21], v[2:3]
	v_mov_b64_e32 v[18:19], v[0:1]
	v_mov_b64_e32 v[16:17], v[14:15]
	v_xor_b32_e32 v247, 64, v249
	v_xor_b32_e32 v246, 0x80, v249
	v_xor_b32_e32 v245, 0xc0, v249
	s_mov_b64 s[16:17], 0
	v_mov_b64_e32 v[14:15], v[12:13]
	v_mov_b64_e32 v[12:13], v[10:11]
	v_mov_b64_e32 v[10:11], v[8:9]
	v_mov_b64_e32 v[8:9], v[6:7]
	v_mov_b64_e32 v[6:7], v[4:5]
	v_mov_b64_e32 v[4:5], v[2:3]
	v_mov_b64_e32 v[2:3], v[0:1]
	s_mov_b32 s19, s15

.LBB0_454:
	s_or_b64 exec, exec, s[10:11]
	v_mov_b32_e32 v0, s80
	s_waitcnt lgkmcnt(0)
	s_barrier
	ds_read_b32 v0, v0
	s_movk_i32 s10, 0x1ff
	s_waitcnt lgkmcnt(0)
	s_barrier
	v_cmp_lt_i32_e32 vcc, s10, v0
	v_readfirstlane_b32 s12, v0
	s_mov_b64 s[10:11], -1
	s_cbranch_vccnz .LBB0_449
	v_mov_b32_e32 v34, v232
	s_and_b32 s51, s12, 7
	v_readfirstlane_b32 s10, v34
	s_ashr_i32 s13, s10, 6
	s_lshl_b32 s10, s12, 8
	s_and_b32 s72, s10, 0x3800
	s_lshl_b32 s10, s12, 2
	s_and_b32 s10, s10, 0xffffff00
	s_lshl_b32 s11, s13, 5
	s_sub_i32 s85, s11, s10
	v_and_b32_e32 v92, 31, v34
	s_addk_i32 s85, 0x700
	v_or_b32_e32 v82, s85, v92
	s_mov_b32 s73, s77
	v_ashrrev_i32_e32 v83, 31, v82
	s_lshl_b32 s14, s51, 6
	v_lshl_add_u64 v[2:3], v[82:83], 0, s[72:73]
	v_mov_b64_e32 v[4:5], s[68:69]
	s_or_b32 s15, s14, 0x800
	v_mad_u64_u32 v[6:7], s[10:11], v2, s83, v[4:5]
	v_bfe_u32 v35, v34, 5, 1
	v_mad_i32_i24 v7, v3, s83, v7
	s_lshl_b32 s58, s15, 1
	s_mov_b32 s59, s77
	v_lshl_add_u64 v[2:3], v[6:7], 0, s[58:59]
	v_lshlrev_b32_e32 v0, 4, v35
	v_lshl_add_u64 v[2:3], v[2:3], 0, v[0:1]
	global_load_dwordx4 v[50:53], v[2:3], off
	global_load_dwordx4 v[54:57], v[2:3], off offset:32
	global_load_dwordx4 v[58:61], v[2:3], off offset:64
	global_load_dwordx4 v[62:65], v[2:3], off offset:96
	s_lshl_b32 s73, s13, 14
	s_or_b32 s16, s14, 0xa00
	s_or_b32 s12, s14, 0xc00
	s_add_i32 s73, s73, 0
	s_ashr_i32 s10, s85, 31
	v_lshrrev_b32_e32 v0, 1, v34
	v_bfe_u32 v83, v34, 3, 3
	s_add_u32 s55, s85, s72
	v_xor_b32_e32 v0, v0, v34
	v_and_b32_e32 v2, 3, v34
	v_and_or_b32 v36, v0, 4, v2
	v_or_b32_e32 v0, s55, v83
	s_addc_u32 s59, s10, 0
	v_mad_u64_u32 v[8:9], s[10:11], v0, s83, v[4:5]
	v_bitop3_b32 v37, v83, v34, 7 bitop3:0x78
	v_mad_i32_i24 v9, s59, v240, v9
	s_lshl_b32 s76, s16, 1
	v_lshl_add_u64 v[2:3], v[8:9], 0, s[76:77]
	v_lshlrev_b32_e32 v0, 4, v37
	v_lshl_add_u64 v[2:3], v[2:3], 0, v[0:1]
	v_or_b32_e32 v93, 8, v83
	v_or_b32_e32 v94, 16, v83
	v_or_b32_e32 v95, 24, v83
	s_lshl_b32 s74, s12, 1
	s_mov_b32 s75, s77
	v_lshl_add_u64 v[8:9], v[8:9], 0, s[74:75]
	s_ashr_i32 s12, s85, 5
	v_lshlrev_b32_e32 v97, 2, v35
	s_barrier
	s_mov_b32 s10, m0
	s_mov_b32 m0, s73
	s_nop 0
	global_load_lds_dwordx4 v[2:3], off
	s_mov_b32 m0, s10
	v_or_b32_e32 v2, s55, v93
	v_mad_u64_u32 v[6:7], s[10:11], v2, s83, v[4:5]
	v_mad_i32_i24 v7, s59, v240, v7
	v_lshl_add_u64 v[2:3], v[6:7], 0, s[76:77]
	v_lshl_add_u64 v[2:3], v[2:3], 0, v[0:1]
	s_add_i32 s10, s73, 0x400
	s_mov_b32 s11, m0
	s_mov_b32 m0, s10
	s_nop 0
	global_load_lds_dwordx4 v[2:3], off
	s_mov_b32 m0, s11
	v_or_b32_e32 v2, s55, v94
	v_mad_u64_u32 v[2:3], s[10:11], v2, s83, v[4:5]
	v_mad_i32_i24 v3, s59, v240, v3
	v_lshl_add_u64 v[10:11], v[2:3], 0, s[76:77]
	v_lshl_add_u64 v[10:11], v[10:11], 0, v[0:1]
	s_add_i32 s10, s73, 0x800
	s_mov_b32 s11, m0
	s_mov_b32 m0, s10
	s_nop 0
	global_load_lds_dwordx4 v[10:11], off
	s_mov_b32 m0, s11
	v_or_b32_e32 v10, s55, v95
	v_mad_u64_u32 v[4:5], s[10:11], v10, s83, v[4:5]
	v_mad_i32_i24 v5, s59, v240, v5
	v_lshl_add_u64 v[10:11], v[4:5], 0, s[76:77]
	v_lshl_add_u64 v[10:11], v[10:11], 0, v[0:1]
	s_add_i32 s10, s73, 0xc00
	s_mov_b32 s11, m0
	s_mov_b32 m0, s10
	s_nop 0
	global_load_lds_dwordx4 v[10:11], off
	s_mov_b32 m0, s11
	v_lshlrev_b32_e32 v0, 4, v36
	v_lshl_add_u64 v[8:9], v[8:9], 0, v[0:1]
	s_add_i32 s10, s73, 0x1000
	s_mov_b32 s11, m0
	s_mov_b32 m0, s10
	s_nop 0
	global_load_lds_dwordx4 v[8:9], off
	s_mov_b32 m0, s11
	v_lshl_add_u64 v[6:7], v[6:7], 0, s[74:75]
	v_lshl_add_u64 v[2:3], v[2:3], 0, s[74:75]
	v_lshl_add_u64 v[6:7], v[6:7], 0, v[0:1]
	s_add_i32 s10, s73, 0x1400
	s_mov_b32 s11, m0
	s_mov_b32 m0, s10
	s_nop 0
	global_load_lds_dwordx4 v[6:7], off
	s_mov_b32 m0, s11
	v_lshl_add_u64 v[2:3], v[2:3], 0, v[0:1]
	s_add_i32 s10, s73, 0x1800
	s_mov_b32 s11, m0
	s_mov_b32 m0, s10
	s_nop 0
	global_load_lds_dwordx4 v[2:3], off
	s_mov_b32 m0, s11
	v_lshl_add_u64 v[2:3], v[4:5], 0, s[74:75]
	v_lshl_add_u64 v[2:3], v[2:3], 0, v[0:1]
	s_add_i32 s10, s73, 0x1c00
	s_mov_b32 s11, m0
	s_mov_b32 m0, s10
	s_nop 0
	global_load_lds_dwordx4 v[2:3], off
	s_mov_b32 m0, s11
	s_mov_b64 s[10:11], -1
	s_cmp_gt_i32 s12, -1
	s_cbranch_scc1 .LBB0_457
	v_lshlrev_b32_e32 v0, 2, v35
	s_mov_b64 s[10:11], 0
